# xcopy 4 rows in flight; P11 wave-local score staging and softmax (4 fewer barriers per token)
# speedup vs baseline: 1.0257x; 1.0027x over previous
; DEVI char* wsp(const Params& P, size_t off) { asm volatile("" : "+s"(off)); return P.ws + off; }
; DEVI int ltid() { int t = threadIdx.x; asm volatile("" : "+v"(t)); return t; }
; DEVI TokInfo tokinfo(int it) {
;   TokInfo r;
;   if (it < 8192) { r.sample = 0; r.seq = it >> 12; r.t = it & 4095; }
;   else if (it < 8448) { int q = it - 8192; r.sample = 1; r.seq = q >> 5; r.t = q & 31; }
;   else { int q = it - 8448; r.sample = 0; r.seq = 2 + (q >> 12); r.t = q & 4095; }
;   return r;
; }
; DEVI void phase_xcopy(const Params& P) {
;   const int tid = ltid();
;   bfu* xb = (bfu*)wsp(P, O_XB);
;   for (int it = blockIdx.x; it < 16640; it += gridDim.x) {
;     TokInfo ti = tokinfo(it);
;     const float* src = ti.sample ? P.in[1] + (long)(ti.seq * 32 + ti.t) * 1024 : P.in[0] + (long)(ti.seq * 4096 + ti.t) * 1024;
;     float* dst = xrow(P, it);
;     int c = tid * 4;
;     float4 v = *reinterpret_cast<const float4*>(src + c);
;     *reinterpret_cast<float4*>(dst + c) = v;
;     uint2 r;
;     r.x = f2b(v.x) | ((unsigned)f2b(v.y) << 16);
;     r.y = f2b(v.z) | ((unsigned)f2b(v.w) << 16);
;     *reinterpret_cast<uint2*>(xb + (long)it * 1024 + c) = r;
;   }
; }
.LBB0_76:
	s_and_b64 vcc, exec, s[40:41]
	s_cbranch_vccz .LBB0_122
	v_readlane_b32 s4, v253, 40
	v_readlane_b32 s5, v253, 41
	v_mov_b32_e32 v0, v93
	s_mov_b64 s[26:27], 0x6502000
	s_andn2_b64 vcc, exec, s[4:5]
	s_cbranch_vccnz .LBB0_96
	v_lshlrev_b32_e32 v4, 2, v0
	v_lshl_add_u64 v[2:3], v[64:65], 0, s[26:27]
	v_ashrrev_i32_e32 v5, 31, v4
	v_lshl_add_u64 v[0:1], v[4:5], 1, v[2:3]
	v_lshlrev_b64 v[2:3], 2, v[4:5]
	s_mov_b32 s26, s74
	v_readlane_b32 s44, v253, 2
	v_readlane_b32 s45, v253, 3
	s_nop 4
	s_load_dwordx4 s[40:43], s[44:45], 0x0
	s_waitcnt lgkmcnt(0)
.Lxc_loop:
	s_mul_i32 s1, s23, 0
	s_add_i32 s1, s1, s26
	s_min_i32 s2, s1, 0x40ff
	s_sub_i32 s24, s2, 0x2000
	s_cmp_lt_u32 s24, 0x100
	s_cselect_b32 s44, s42, s40
	s_cselect_b32 s45, s43, s41
	s_cselect_b32 s27, s24, s2
	s_sub_i32 s46, s27, 0x100
	s_cmp_gt_i32 s2, 0x20ff
	s_cselect_b32 s27, s46, s27
	s_lshl_b32 s27, s27, 12
	s_add_u32 s44, s44, s27
	s_addc_u32 s45, s45, 0
	v_lshl_add_u64 v[20:21], s[44:45], 0, v[2:3]
	global_load_dwordx4 v[4:7], v[20:21], off
	s_mul_i32 s1, s23, 1
	s_add_i32 s1, s1, s26
	s_min_i32 s2, s1, 0x40ff
	s_sub_i32 s24, s2, 0x2000
	s_cmp_lt_u32 s24, 0x100
	s_cselect_b32 s44, s42, s40
	s_cselect_b32 s45, s43, s41
	s_cselect_b32 s27, s24, s2
	s_sub_i32 s46, s27, 0x100
	s_cmp_gt_i32 s2, 0x20ff
	s_cselect_b32 s27, s46, s27
	s_lshl_b32 s27, s27, 12
	s_add_u32 s44, s44, s27
	s_addc_u32 s45, s45, 0
	v_lshl_add_u64 v[20:21], s[44:45], 0, v[2:3]
	global_load_dwordx4 v[8:11], v[20:21], off
	s_mul_i32 s1, s23, 2
	s_add_i32 s1, s1, s26
	s_min_i32 s2, s1, 0x40ff
	s_sub_i32 s24, s2, 0x2000
	s_cmp_lt_u32 s24, 0x100
	s_cselect_b32 s44, s42, s40
	s_cselect_b32 s45, s43, s41
	s_cselect_b32 s27, s24, s2
	s_sub_i32 s46, s27, 0x100
	s_cmp_gt_i32 s2, 0x20ff
	s_cselect_b32 s27, s46, s27
	s_lshl_b32 s27, s27, 12
	s_add_u32 s44, s44, s27
	s_addc_u32 s45, s45, 0
	v_lshl_add_u64 v[20:21], s[44:45], 0, v[2:3]
	global_load_dwordx4 v[12:15], v[20:21], off
	s_mul_i32 s1, s23, 3
	s_add_i32 s1, s1, s26
	s_min_i32 s2, s1, 0x40ff
	s_sub_i32 s24, s2, 0x2000
	s_cmp_lt_u32 s24, 0x100
	s_cselect_b32 s44, s42, s40
	s_cselect_b32 s45, s43, s41
	s_cselect_b32 s27, s24, s2
	s_sub_i32 s46, s27, 0x100
	s_cmp_gt_i32 s2, 0x20ff
	s_cselect_b32 s27, s46, s27
	s_lshl_b32 s27, s27, 12
	s_add_u32 s44, s44, s27
	s_addc_u32 s45, s45, 0
	v_lshl_add_u64 v[20:21], s[44:45], 0, v[2:3]
	global_load_dwordx4 v[16:19], v[20:21], off
	s_mul_i32 s1, s23, 0
	s_add_i32 s1, s1, s26
	s_cmpk_ge_i32 s1, 0x4100
	s_cbranch_scc1 .Lxc_exit
	s_sub_i32 s24, s1, 0x2000
	s_cmp_lt_u32 s24, 0x100
	s_cselect_b32 s44, s33, s28
	s_cselect_b32 s45, s93, s29
	s_cselect_b32 s27, s24, s1
	s_sub_i32 s46, s27, 0x100
	s_cmp_gt_i32 s1, 0x20ff
	s_cselect_b32 s27, s46, s27
	s_lshl_b32 s27, s27, 12
	s_add_u32 s44, s44, s27
	s_addc_u32 s45, s45, 0
	v_lshl_add_u64 v[20:21], s[44:45], 0, v[2:3]
	s_ashr_i32 s47, s1, 31
	s_mov_b32 s46, s1
	s_lshl_b64 s[46:47], s[46:47], 11
	s_waitcnt vmcnt(3)
	v_and_b32_sdwa v22, v6, v95 dst_sel:DWORD dst_unused:UNUSED_PAD src0_sel:WORD_1 src1_sel:DWORD
	v_and_b32_sdwa v23, v4, v95 dst_sel:DWORD dst_unused:UNUSED_PAD src0_sel:WORD_1 src1_sel:DWORD
	global_store_dwordx4 v[20:21], v[4:7], off
	v_lshl_add_u64 v[20:21], v[0:1], 0, s[46:47]
	s_nop 0
	v_add3_u32 v4, v4, v23, s39
	v_add3_u32 v6, v6, v22, s39
	v_and_b32_sdwa v22, v7, v95 dst_sel:DWORD dst_unused:UNUSED_PAD src0_sel:WORD_1 src1_sel:DWORD
	v_and_b32_sdwa v23, v5, v95 dst_sel:DWORD dst_unused:UNUSED_PAD src0_sel:WORD_1 src1_sel:DWORD
	v_add3_u32 v7, v7, v22, s39
	v_add3_u32 v5, v5, v23, s39
	v_and_b32_e32 v7, 0xffff0000, v7
	v_and_b32_e32 v22, 0xffff0000, v5
	v_or_b32_sdwa v5, v7, v6 dst_sel:DWORD dst_unused:UNUSED_PAD src0_sel:DWORD src1_sel:WORD_1
	v_or_b32_sdwa v4, v22, v4 dst_sel:DWORD dst_unused:UNUSED_PAD src0_sel:DWORD src1_sel:WORD_1
	global_store_dwordx2 v[20:21], v[4:5], off
	s_mul_i32 s1, s23, 1
	s_add_i32 s1, s1, s26
	s_cmpk_ge_i32 s1, 0x4100
	s_cbranch_scc1 .Lxc_exit
; DEVI char* wsp(const Params& P, size_t off) { asm volatile("" : "+s"(off)); return P.ws + off; }
; DEVI int ltid() { int t = threadIdx.x; asm volatile("" : "+v"(t)); return t; }
; DEVI void phase_xcopy(const Params& P) {
;   const int tid = ltid();
;   bfu* xb = (bfu*)wsp(P, O_XB);
;   for (int it = blockIdx.x; it < 16640; it += gridDim.x) {
;     TokInfo ti = tokinfo(it);
;     const float* src = ti.sample ? P.in[1] + (long)(ti.seq * 32 + ti.t) * 1024 : P.in[0] + (long)(ti.seq * 4096 + ti.t) * 1024;
;     float* dst = xrow(P, it);
;     int c = tid * 4;
;     float4 v = *reinterpret_cast<const float4*>(src + c);
;     *reinterpret_cast<float4*>(dst + c) = v;
;     uint2 r;
;     r.x = f2b(v.x) | ((unsigned)f2b(v.y) << 16);
;     r.y = f2b(v.z) | ((unsigned)f2b(v.w) << 16);
;     *reinterpret_cast<uint2*>(xb + (long)it * 1024 + c) = r;
;   }
; }
; __global__ void __launch_bounds__(256, 2) fwd_megakernel(Params P) {
;     ...
;       grid.sync();
	s_sub_i32 s24, s1, 0x2000
	s_cmp_lt_u32 s24, 0x100
	s_cselect_b32 s44, s33, s28
	s_cselect_b32 s45, s93, s29
	s_cselect_b32 s27, s24, s1
	s_sub_i32 s46, s27, 0x100
	s_cmp_gt_i32 s1, 0x20ff
	s_cselect_b32 s27, s46, s27
	s_lshl_b32 s27, s27, 12
	s_add_u32 s44, s44, s27
	s_addc_u32 s45, s45, 0
	v_lshl_add_u64 v[20:21], s[44:45], 0, v[2:3]
	s_ashr_i32 s47, s1, 31
	s_mov_b32 s46, s1
	s_lshl_b64 s[46:47], s[46:47], 11
	s_waitcnt vmcnt(4)
	v_and_b32_sdwa v22, v10, v95 dst_sel:DWORD dst_unused:UNUSED_PAD src0_sel:WORD_1 src1_sel:DWORD
	v_and_b32_sdwa v23, v8, v95 dst_sel:DWORD dst_unused:UNUSED_PAD src0_sel:WORD_1 src1_sel:DWORD
	global_store_dwordx4 v[20:21], v[8:11], off
	v_lshl_add_u64 v[20:21], v[0:1], 0, s[46:47]
	s_nop 0
	v_add3_u32 v8, v8, v23, s39
	v_add3_u32 v10, v10, v22, s39
	v_and_b32_sdwa v22, v11, v95 dst_sel:DWORD dst_unused:UNUSED_PAD src0_sel:WORD_1 src1_sel:DWORD
	v_and_b32_sdwa v23, v9, v95 dst_sel:DWORD dst_unused:UNUSED_PAD src0_sel:WORD_1 src1_sel:DWORD
	v_add3_u32 v11, v11, v22, s39
	v_add3_u32 v9, v9, v23, s39
	v_and_b32_e32 v11, 0xffff0000, v11
	v_and_b32_e32 v22, 0xffff0000, v9
	v_or_b32_sdwa v9, v11, v10 dst_sel:DWORD dst_unused:UNUSED_PAD src0_sel:DWORD src1_sel:WORD_1
	v_or_b32_sdwa v8, v22, v8 dst_sel:DWORD dst_unused:UNUSED_PAD src0_sel:DWORD src1_sel:WORD_1
	global_store_dwordx2 v[20:21], v[8:9], off
	s_mul_i32 s1, s23, 2
	s_add_i32 s1, s1, s26
	s_cmpk_ge_i32 s1, 0x4100
	s_cbranch_scc1 .Lxc_exit
	s_sub_i32 s24, s1, 0x2000
	s_cmp_lt_u32 s24, 0x100
	s_cselect_b32 s44, s33, s28
	s_cselect_b32 s45, s93, s29
	s_cselect_b32 s27, s24, s1
	s_sub_i32 s46, s27, 0x100
	s_cmp_gt_i32 s1, 0x20ff
	s_cselect_b32 s27, s46, s27
	s_lshl_b32 s27, s27, 12
	s_add_u32 s44, s44, s27
	s_addc_u32 s45, s45, 0
	v_lshl_add_u64 v[20:21], s[44:45], 0, v[2:3]
	s_ashr_i32 s47, s1, 31
	s_mov_b32 s46, s1
	s_lshl_b64 s[46:47], s[46:47], 11
	s_waitcnt vmcnt(5)
	v_and_b32_sdwa v22, v14, v95 dst_sel:DWORD dst_unused:UNUSED_PAD src0_sel:WORD_1 src1_sel:DWORD
	v_and_b32_sdwa v23, v12, v95 dst_sel:DWORD dst_unused:UNUSED_PAD src0_sel:WORD_1 src1_sel:DWORD
	global_store_dwordx4 v[20:21], v[12:15], off
	v_lshl_add_u64 v[20:21], v[0:1], 0, s[46:47]
	s_nop 0
	v_add3_u32 v12, v12, v23, s39
	v_add3_u32 v14, v14, v22, s39
	v_and_b32_sdwa v22, v15, v95 dst_sel:DWORD dst_unused:UNUSED_PAD src0_sel:WORD_1 src1_sel:DWORD
	v_and_b32_sdwa v23, v13, v95 dst_sel:DWORD dst_unused:UNUSED_PAD src0_sel:WORD_1 src1_sel:DWORD
	v_add3_u32 v15, v15, v22, s39
	v_add3_u32 v13, v13, v23, s39
	v_and_b32_e32 v15, 0xffff0000, v15
	v_and_b32_e32 v22, 0xffff0000, v13
	v_or_b32_sdwa v13, v15, v14 dst_sel:DWORD dst_unused:UNUSED_PAD src0_sel:DWORD src1_sel:WORD_1
	v_or_b32_sdwa v12, v22, v12 dst_sel:DWORD dst_unused:UNUSED_PAD src0_sel:DWORD src1_sel:WORD_1
	global_store_dwordx2 v[20:21], v[12:13], off
	s_mul_i32 s1, s23, 3
	s_add_i32 s1, s1, s26
	s_cmpk_ge_i32 s1, 0x4100
	s_cbranch_scc1 .Lxc_exit
	s_sub_i32 s24, s1, 0x2000
	s_cmp_lt_u32 s24, 0x100
	s_cselect_b32 s44, s33, s28
	s_cselect_b32 s45, s93, s29
	s_cselect_b32 s27, s24, s1
	s_sub_i32 s46, s27, 0x100
	s_cmp_gt_i32 s1, 0x20ff
	s_cselect_b32 s27, s46, s27
	s_lshl_b32 s27, s27, 12
	s_add_u32 s44, s44, s27
	s_addc_u32 s45, s45, 0
	v_lshl_add_u64 v[20:21], s[44:45], 0, v[2:3]
	s_ashr_i32 s47, s1, 31
	s_mov_b32 s46, s1
	s_lshl_b64 s[46:47], s[46:47], 11
	s_waitcnt vmcnt(6)
	v_and_b32_sdwa v22, v18, v95 dst_sel:DWORD dst_unused:UNUSED_PAD src0_sel:WORD_1 src1_sel:DWORD
	v_and_b32_sdwa v23, v16, v95 dst_sel:DWORD dst_unused:UNUSED_PAD src0_sel:WORD_1 src1_sel:DWORD
	global_store_dwordx4 v[20:21], v[16:19], off
	v_lshl_add_u64 v[20:21], v[0:1], 0, s[46:47]
	s_nop 0
	v_add3_u32 v16, v16, v23, s39
	v_add3_u32 v18, v18, v22, s39
	v_and_b32_sdwa v22, v19, v95 dst_sel:DWORD dst_unused:UNUSED_PAD src0_sel:WORD_1 src1_sel:DWORD
	v_and_b32_sdwa v23, v17, v95 dst_sel:DWORD dst_unused:UNUSED_PAD src0_sel:WORD_1 src1_sel:DWORD
	v_add3_u32 v19, v19, v22, s39
	v_add3_u32 v17, v17, v23, s39
	v_and_b32_e32 v19, 0xffff0000, v19
	v_and_b32_e32 v22, 0xffff0000, v17
	v_or_b32_sdwa v17, v19, v18 dst_sel:DWORD dst_unused:UNUSED_PAD src0_sel:DWORD src1_sel:WORD_1
	v_or_b32_sdwa v16, v22, v16 dst_sel:DWORD dst_unused:UNUSED_PAD src0_sel:DWORD src1_sel:WORD_1
	global_store_dwordx2 v[20:21], v[16:17], off
	s_lshl_b32 s1, s23, 2
	s_add_i32 s26, s26, s1
	s_cmpk_lt_i32 s26, 0x4100
	s_cbranch_scc1 .Lxc_loop
.Lxc_exit:
	s_waitcnt vmcnt(0)
.LBB0_96:
	v_readlane_b32 s4, v253, 42
	v_readlane_b32 s5, v253, 43
	s_barrier
	s_and_saveexec_b64 s[26:27], s[4:5]
	s_cbranch_execz .LBB0_106
	v_readlane_b32 s40, v253, 0
	v_readlane_b32 s41, v253, 1
	buffer_wbl2 sc1
	s_waitcnt vmcnt(0)
	s_load_dwordx2 s[40:41], s[40:41], 0x58
	s_mov_b64 s[42:43], exec
	v_mbcnt_lo_u32_b32 v1, s42, 0
	v_mbcnt_hi_u32_b32 v1, s43, v1
	v_cmp_eq_u32_e32 vcc, 0, v1
	s_waitcnt lgkmcnt(0)
	global_load_dword v0, v89, s[40:41] offset:40
	s_and_saveexec_b64 s[44:45], vcc
	s_cbranch_execz .LBB0_99
	s_bcnt1_i32_b64 s1, s[42:43]
	v_mov_b32_e32 v2, s1
	global_atomic_add v2, v89, v2, s[40:41] offset:32 sc0

; DEVI int ltid() { int t = threadIdx.x; asm volatile("" : "+v"(t)); return t; }
; DEVI void phase11(const Params& P, int l, int pass, char* smem) {
;   const int ntok = pass ? 8192 : 8448, base = pass ? 8448 : 0;
;   const int tid = ltid(); const int w = tid >> 6, lane = tid & 63;
;   float* scl = (float*)smem;
;   float* sv = scl + 2048;
;   int* si = (int*)(sv + 256);
;   float* tops = (float*)(si + 256);
;   int* tope = (int*)(tops + 128);
;   float* wgt = (float*)(tope + 128);
;   float* svs = wgt + 128;
;   int* sis = (int*)(svs + 256);
;   float* red = (float*)(sis + 256);
;   float* stat = red + 4096;
;   const float* SC = (const float*)(P.ws + O_AU);
;   const unsigned char* UT = (const unsigned char*)(P.ws + O_UTB);
;   const unsigned char* VTb = (const unsigned char*)(P.ws + O_VTB);
;   const float* g2 = P.in[28] + l * 1024;
;   const float* b2 = P.in[29] + l * 1024;
;   bfu* xb = (bfu*)(P.ws + O_XB);
;   const unsigned long long ltmask = (1ull << lane) - 1ull;
;   for (int lt = blockIdx.x; lt < ntok; lt += gridDim.x) {
;     const int it = base + lt;
;     float* xr = xrow(P, it);
;     __syncthreads();
;     {
;       unsigned long long* s8 = reinterpret_cast<unsigned long long*>(const_cast<float*>(SC) + (long)lt * 2048);
;       unsigned long long* d8 = reinterpret_cast<unsigned long long*>(scl);
; #pragma unroll
;       for (int q = 0; q < 4; ++q)
;         d8[tid + 256 * q] = __hip_atomic_load(s8 + tid + 256 * q, __ATOMIC_RELAXED, __HIP_MEMORY_SCOPE_AGENT);
;     }
;     __syncthreads();
;     {
;       float v0[4], v1[4]; unsigned k0[4], k1[4], T[4];
; #pragma unroll
;       for (int li = 0; li < 4; ++li) {
;         const int Lx = w * 4 + li;
;         v0[li] = scl[Lx * 128 + lane]; v1[li] = scl[Lx * 128 + 64 + lane];
.LBB0_125:
	s_andn2_b64 vcc, exec, s[26:27]
	s_mov_b32 s0, s2
	s_cbranch_vccnz .LBB0_276
	s_add_i32 s1, s51, -1
	s_mov_b32 s0, s2
	s_cmp_eq_u32 s1, 0
	s_cselect_b64 s[40:41], -1, 0
	s_and_b64 s[42:43], s[40:41], exec
	s_movk_i32 s1, 0x2100
	s_cselect_b32 s1, s1, 0x2000
	v_readlane_b32 s58, v252, 32
	v_mov_b32_e32 v0, v93
	s_cmp_ge_i32 s58, s1
	s_cbranch_scc1 .LBB0_276
	v_and_b32_e32 v88, 63, v0
	v_lshlrev_b64 v[2:3], v0, -1
	v_not_b32_e32 v91, v3
	v_not_b32_e32 v100, v2
	v_lshlrev_b32_e32 v2, 4, v88
	v_mov_b32_e32 v3, v89
	v_lshl_add_u64 v[110:111], v[70:71], 0, v[2:3]
	v_lshl_add_u64 v[112:113], v[68:69], 0, v[2:3]
	v_and_b32_e32 v3, 32, v0
	v_and_b32_e32 v4, 64, v187
	v_cmp_eq_u32_e64 s[44:45], 0, v3
	v_xor_b32_e32 v3, 32, v187
	v_add_u32_e32 v4, 64, v4
	v_cmp_lt_i32_e32 vcc, v3, v4
	v_and_b32_e32 v7, 15, v0
	s_and_b64 s[40:41], s[40:41], exec
	v_cndmask_b32_e32 v3, v187, v3, vcc
	v_lshlrev_b32_e32 v125, 2, v3
	v_and_b32_e32 v3, 16, v0
	v_cmp_eq_u32_e64 s[46:47], 0, v3
	v_xor_b32_e32 v3, 16, v187
	v_cmp_lt_i32_e32 vcc, v3, v4
	s_cselect_b32 s82, 0, 0x2100
	s_lshl_b32 s40, s0, 10
	v_cndmask_b32_e32 v3, v187, v3, vcc
	v_lshlrev_b32_e32 v126, 2, v3
	v_and_b32_e32 v3, 8, v0
	v_cmp_eq_u32_e64 s[48:49], 0, v3
	v_xor_b32_e32 v3, 8, v187
	v_cmp_lt_i32_e32 vcc, v3, v4
	s_ashr_i32 s41, s40, 31
	v_readlane_b32 s4, v253, 14
	v_cndmask_b32_e32 v3, v187, v3, vcc
	v_lshlrev_b32_e32 v127, 2, v3
	v_xor_b32_e32 v3, 4, v187
	v_cmp_lt_i32_e32 vcc, v3, v4
	s_lshl_b64 s[40:41], s[40:41], 2
	v_readlane_b32 s18, v253, 28
	v_cndmask_b32_e32 v3, v187, v3, vcc
	v_lshlrev_b32_e32 v128, 2, v3
	v_xor_b32_e32 v3, 2, v187
	v_cmp_lt_i32_e32 vcc, v3, v4
	v_readlane_b32 s19, v253, 29
	s_add_u32 s54, s18, s40
	v_cndmask_b32_e32 v3, v187, v3, vcc
	v_lshlrev_b32_e32 v129, 2, v3
	v_xor_b32_e32 v3, 1, v187
	v_cmp_lt_i32_e32 vcc, v3, v4
	v_readlane_b32 s16, v253, 26
	s_addc_u32 s55, s19, s41
	v_cndmask_b32_e32 v3, v187, v3, vcc
	v_cmp_ne_u32_e32 vcc, 0, v7
	v_readlane_b32 s17, v253, 27
	s_add_u32 s56, s16, s40
	v_cndmask_b32_e64 v132, 0, 1, vcc
	v_cmp_lt_u32_e32 vcc, 1, v7
	v_ashrrev_i32_e32 v6, 6, v0
	s_addc_u32 s57, s17, s41
	v_cndmask_b32_e64 v133, 0, 1, vcc
	v_cmp_lt_u32_e32 vcc, 2, v7
	v_and_b32_e32 v109, 0xffffffc0, v0
	v_lshlrev_b32_e32 v104, 2, v0
	v_cndmask_b32_e64 v134, 0, 1, vcc
	v_cmp_lt_u32_e32 vcc, 3, v7
	v_lshlrev_b32_e32 v108, 7, v6
	s_movk_i32 s24, 0xf80
	v_cndmask_b32_e64 v135, 0, 1, vcc
	v_cmp_lt_u32_e32 vcc, 4, v7
	v_readlane_b32 s6, v253, 16
	v_readlane_b32 s7, v253, 17
	v_cndmask_b32_e64 v136, 0, 1, vcc
	v_cmp_lt_u32_e32 vcc, 5, v7
	v_ashrrev_i32_e32 v1, 31, v0
	v_lshlrev_b32_e32 v101, 3, v0
	v_cndmask_b32_e64 v137, 0, 1, vcc
	v_cmp_lt_u32_e32 vcc, 6, v7
	s_getpc_b64 s[42:43]
	s_add_u32 s42, s42, CAND_IJ@rel32@lo+4
	s_addc_u32 s43, s43, CAND_IJ@rel32@hi+12
	v_cndmask_b32_e64 v138, 0, 1, vcc
	v_cmp_lt_u32_e32 vcc, 7, v7
	s_movk_i32 s4, 0x80
	v_lshlrev_b32_e32 v130, 2, v3
	v_cndmask_b32_e64 v139, 0, 1, vcc
	v_cmp_lt_u32_e32 vcc, 8, v7
	v_and_b32_e32 v3, 7, v0
	v_mad_u64_u32 v[4:5], s[52:53], v6, s24, v[108:109]
	v_cndmask_b32_e64 v140, 0, 1, vcc
	v_cmp_lt_u32_e32 vcc, 9, v7
	v_ashrrev_i32_e32 v105, 31, v104
	s_movk_i32 s24, 0xf004
	v_cndmask_b32_e64 v141, 0, 1, vcc
	v_cmp_lt_u32_e32 vcc, 10, v7
	v_readlane_b32 s6, v252, 37
	v_lshlrev_b32_e32 v8, 2, v88
	v_cndmask_b32_e64 v142, 0, 1, vcc
	v_cmp_lt_u32_e32 vcc, 11, v7
	v_lshl_add_u64 v[102:103], v[0:1], 3, v[72:73]
	v_lshlrev_b32_e32 v1, 11, v6
	v_cndmask_b32_e64 v143, 0, 1, vcc
	v_cmp_lt_u32_e32 vcc, 12, v7
	v_and_b32_e32 v121, -16, v0
	v_sub_u32_e32 v122, v101, v104
	v_cndmask_b32_e64 v144, 0, 1, vcc
	v_cmp_lt_u32_e32 vcc, 13, v7
	v_lshl_add_u64 v[106:107], s[42:43], 0, v[88:89]
	v_lshlrev_b32_e32 v124, 5, v6
	v_cmp_gt_u32_e64 s[42:43], 32, v88
	v_cmp_eq_u32_e64 s[50:51], 0, v3
	v_mul_lo_u32 v3, v0, 12
	v_mul_lo_u32 v5, v6, s24
	v_cndmask_b32_e64 v145, 0, 1, vcc
	v_cmp_eq_u32_e32 vcc, 15, v7
	v_lshlrev_b64 v[6:7], 2, v[104:105]
	v_lshrrev_b32_e32 v0, 1, v0
	v_readlane_b32 s7, v252, 38
	v_readlane_b32 s23, v252, 31
	v_or_b32_e32 v120, 64, v88
	v_lshlrev_b32_e32 v123, 2, v121
	v_cmp_gt_u32_e64 s[40:41], 50, v88
	v_lshl_add_u32 v131, v88, 6, v4
	v_cmp_eq_u32_e64 s[52:53], 0, v88
	v_lshl_add_u64 v[114:115], v[104:105], 1, v[66:67]
	v_cndmask_b32_e64 v146, 0, 1, vcc
	v_lshl_add_u64 v[116:117], s[56:57], 0, v[6:7]
	v_lshl_add_u64 v[118:119], s[54:55], 0, v[6:7]
	v_add_u32_e32 v147, 0x2800, v108
	v_and_b32_e32 v148, 28, v0
	v_add_u32_e32 v149, v8, v1
	v_lshlrev_b32_e32 v150, 2, v2
	v_add_u32_e32 v151, v122, v3
	v_add_u32_e32 v152, v4, v5
	s_mov_b32 s74, s58
	v_readlane_b32 s5, v253, 15
	v_readlane_b32 s8, v253, 18
	v_readlane_b32 s9, v253, 19
	v_readlane_b32 s10, v253, 20
	v_readlane_b32 s11, v253, 21
	v_readlane_b32 s12, v253, 22
	v_readlane_b32 s13, v253, 23
	v_readlane_b32 s14, v253, 24
	v_readlane_b32 s15, v253, 25
	v_lshlrev_b32_e32 v232, 2, v104
	v_lshlrev_b32_e32 v250, 4, v88
	v_mov_b32_e32 v233, 0
	s_and_saveexec_b64 s[54:55], s[40:41]
	global_load_ubyte v233, v[106:107], off
	s_or_b64 exec, exec, s[54:55]
	v_lshrrev_b32_e32 v251, 6, v93
	v_mul_u32_u24_e32 v251, 0x600, v251
	v_add_u32_e32 v101, v101, v251
	v_add_co_u32_e32 v102, vcc, v102, v251
	s_nop 1
	v_addc_co_u32_e32 v103, vcc, 0, v103, vcc
	s_mov_b32 s54, s74
	s_ashr_i32 s55, s74, 31
	s_lshl_b64 s[54:55], s[54:55], 13
	v_lshl_add_u64 v[218:219], v[102:103], 0, s[54:55]
	global_load_dwordx2 v[210:211], v[218:219], off sc1
	global_load_dwordx2 v[212:213], v[218:219], off offset:512 sc1
	global_load_dwordx2 v[214:215], v[218:219], off offset:1024 sc1
	global_load_dwordx2 v[216:217], v[218:219], off offset:1536 sc1
	global_load_dwordx4 v[220:223], v[116:117], off
	global_load_dwordx4 v[224:227], v[118:119], off
	s_branch .LBB0_129

; DEVI void phase11(const Params& P, int l, int pass, char* smem) {
;     ...
;     __syncthreads();
;     {
;       unsigned long long* s8 = reinterpret_cast<unsigned long long*>(const_cast<float*>(SC) + (long)lt * 2048);
;       unsigned long long* d8 = reinterpret_cast<unsigned long long*>(scl);
; #pragma unroll
;       for (int q = 0; q < 4; ++q)
;         d8[tid + 256 * q] = __hip_atomic_load(s8 + tid + 256 * q, __ATOMIC_RELAXED, __HIP_MEMORY_SCOPE_AGENT);
;     }
;     __syncthreads();
;     {
;       float v0[4], v1[4]; unsigned k0[4], k1[4], T[4];
; #pragma unroll
;       for (int li = 0; li < 4; ++li) {
;         const int Lx = w * 4 + li;
;         v0[li] = scl[Lx * 128 + lane]; v1[li] = scl[Lx * 128 + 64 + lane];
;         k0[li] = fkey(v0[li]); k1[li] = fkey(v1[li]); T[li] = 0;
;       }
.LBB0_137:
	s_mov_b32 s62, 0
	s_mov_b32 s84, 0
	s_mov_b32 s24, 0
	s_mov_b32 s75, 0
	s_waitcnt vmcnt(2)
	ds_write_b64 v101, v[210:211]
	ds_write_b64 v101, v[212:213] offset:512
	ds_write_b64 v101, v[214:215] offset:1024
	ds_write_b64 v101, v[216:217] offset:1536
	s_waitcnt lgkmcnt(0)
	ds_read2st64_b32 v[10:11], v149 offset1:1
	ds_read2st64_b32 v[6:7], v149 offset0:2 offset1:3
	s_waitcnt lgkmcnt(1)
	v_and_b32_e32 v1, 0x7fffffff, v10
	v_and_b32_e32 v0, 0x7fffffff, v11
	v_xor_b32_e32 v2, -1, v10
	v_xor_b32_e32 v3, -1, v11
	v_pk_add_f32 v[0:1], v[0:1], 0 neg_lo:[1,1] neg_hi:[1,1]
	v_cmp_gt_i32_e32 vcc, 0, v11
	v_cmp_gt_i32_e64 s[54:55], 0, v10
	s_nop 0
	v_cndmask_b32_e32 v14, v0, v3, vcc
	v_cndmask_b32_e64 v15, v1, v2, s[54:55]
	s_waitcnt lgkmcnt(0)
	v_and_b32_e32 v1, 0x7fffffff, v6
	v_and_b32_e32 v0, 0x7fffffff, v7
	v_xor_b32_e32 v2, -1, v6
	v_xor_b32_e32 v3, -1, v7
	v_pk_add_f32 v[0:1], v[0:1], 0 neg_lo:[1,1] neg_hi:[1,1]
	v_cmp_gt_i32_e32 vcc, 0, v7
	v_cmp_gt_i32_e64 s[54:55], 0, v6
	s_nop 0
	v_cndmask_b32_e32 v12, v0, v3, vcc
	v_cndmask_b32_e64 v13, v1, v2, s[54:55]
	ds_read2st64_b32 v[2:3], v149 offset0:4 offset1:5
	s_waitcnt lgkmcnt(0)
	v_and_b32_e32 v1, 0x7fffffff, v2
	v_and_b32_e32 v0, 0x7fffffff, v3
	v_xor_b32_e32 v4, -1, v2
	v_xor_b32_e32 v5, -1, v3
	v_pk_add_f32 v[0:1], v[0:1], 0 neg_lo:[1,1] neg_hi:[1,1]
	v_cmp_gt_i32_e32 vcc, 0, v3
	v_cmp_gt_i32_e64 s[54:55], 0, v2
	s_nop 0
	v_cndmask_b32_e32 v8, v0, v5, vcc
	v_cndmask_b32_e64 v9, v1, v4, s[54:55]
	ds_read2st64_b32 v[0:1], v149 offset0:6 offset1:7
	s_waitcnt lgkmcnt(0)
	v_and_b32_e32 v5, 0x7fffffff, v0
	v_and_b32_e32 v4, 0x7fffffff, v1
	v_xor_b32_e32 v16, -1, v0
	v_xor_b32_e32 v17, -1, v1
	v_pk_add_f32 v[4:5], v[4:5], 0 neg_lo:[1,1] neg_hi:[1,1]
	v_cmp_gt_i32_e32 vcc, 0, v1
	v_cmp_gt_i32_e64 s[54:55], 0, v0
	s_nop 0
	v_cndmask_b32_e32 v4, v4, v17, vcc
	v_cndmask_b32_e64 v5, v5, v16, s[54:55]
	s_mov_b32 s54, 31

; DEVI void phase11(const Params& P, int l, int pass, char* smem) {
;     ...
;     __syncthreads();
;     if (tid < 128) {
;       float s = tops[tid];
;       float mx = s;
;       mx = fmaxf(mx, __shfl_xor(mx, 1)); mx = fmaxf(mx, __shfl_xor(mx, 2));
;       mx = fmaxf(mx, __shfl_xor(mx, 4)); mx = fmaxf(mx, __shfl_xor(mx, 8));
;       float e = __expf(s - mx);
;       float sm = e;
;       sm += __shfl_xor(sm, 1); sm += __shfl_xor(sm, 2); sm += __shfl_xor(sm, 4); sm += __shfl_xor(sm, 8);
;       tops[tid] = e / sm;
;     }
;     __syncthreads();
.LBB0_261:
	s_or_b64 exec, exec, s[54:55]
	s_waitcnt lgkmcnt(0)
	s_and_saveexec_b64 s[54:55], s[42:43]
	s_cbranch_execz .LBB0_263
	v_sub_u32_e32 v8, v122, v108
	ds_read_b32 v0, v8 offset:10240
	s_waitcnt lgkmcnt(0)
	ds_bpermute_b32 v1, v130, v0
	v_max_f32_e32 v2, v0, v0
	s_waitcnt lgkmcnt(0)
	v_max_f32_e32 v1, v1, v1
	v_max_f32_e32 v1, v2, v1
	ds_bpermute_b32 v2, v129, v1
	s_waitcnt lgkmcnt(0)
	v_max_f32_e32 v2, v2, v2
	v_max_f32_e32 v1, v1, v2
	ds_bpermute_b32 v2, v128, v1
	s_waitcnt lgkmcnt(0)
	v_max_f32_e32 v2, v2, v2
	v_max_f32_e32 v1, v1, v2
	ds_bpermute_b32 v2, v127, v1
	s_waitcnt lgkmcnt(0)
	v_max_f32_e32 v2, v2, v2
	v_max_f32_e32 v1, v1, v2
	v_sub_f32_e32 v0, v0, v1
	v_mul_f32_e32 v0, 0x3fb8aa3b, v0
	v_exp_f32_e32 v0, v0
	ds_bpermute_b32 v1, v130, v0
	s_waitcnt lgkmcnt(0)
	v_add_f32_e32 v1, v0, v1
	ds_bpermute_b32 v2, v129, v1
	s_waitcnt lgkmcnt(0)
	v_add_f32_e32 v1, v1, v2
	ds_bpermute_b32 v2, v128, v1
	s_waitcnt lgkmcnt(0)
	v_add_f32_e32 v1, v1, v2
	ds_bpermute_b32 v2, v127, v1
	s_waitcnt lgkmcnt(0)
	v_add_f32_e32 v1, v1, v2
	v_div_scale_f32 v2, s[56:57], v1, v1, v0
	v_rcp_f32_e32 v3, v2
	v_div_scale_f32 v4, vcc, v0, v1, v0
	v_fma_f32 v5, -v2, v3, 1.0
	v_fmac_f32_e32 v3, v5, v3
	v_mul_f32_e32 v5, v4, v3
	v_fma_f32 v6, -v2, v5, v4
	v_fmac_f32_e32 v5, v6, v3
	v_fma_f32 v2, -v2, v5, v4
	v_div_fmas_f32 v2, v2, v3, v5
	v_div_fixup_f32 v0, v2, v1, v0
	ds_write_b32 v8, v0 offset:10240
.LBB0_263:
	s_or_b64 exec, exec, s[54:55]
	s_lshl_b32 s24, s77, 12
	s_lshl_b32 s54, s77, 5
	s_or_b32 s24, s24, s83
	s_add_i32 s56, s54, s83
	s_and_b64 s[54:55], s[78:79], exec
	s_cselect_b32 s54, s24, s56
	s_ashr_i32 s55, s54, 31
	s_lshl_b64 s[54:55], s[54:55], 12
	s_and_b64 s[56:57], s[78:79], exec
	s_cselect_b32 s56, s28, s33
	s_cselect_b32 s24, s29, s93
	s_add_u32 s54, s56, s54
	s_addc_u32 s55, s24, s55
	s_waitcnt lgkmcnt(0)
	v_readfirstlane_b32 s60, v110
	v_readfirstlane_b32 s61, v111
	v_readfirstlane_b32 s62, v112
	v_readfirstlane_b32 s63, v113
	global_load_dwordx4 v[0:3], v150, s[54:55] offset:48
	global_load_dwordx4 v[4:7], v150, s[54:55] offset:32
	global_load_dwordx4 v[8:11], v150, s[54:55] offset:16
	global_load_dwordx4 v[12:15], v150, s[54:55]
	global_load_dwordx4 v[228:231], v232, s[54:55]
	v_mov_b32_e32 v16, 0
	s_mov_b32 s24, -8
	v_mov_b32_e32 v153, v147
	v_mov_b32_e32 v17, v16
	v_mov_b32_e32 v18, v16
	v_mov_b32_e32 v19, v16
	v_mov_b32_e32 v28, v16
	v_mov_b32_e32 v29, v16
	v_mov_b32_e32 v30, v16
	v_mov_b32_e32 v31, v16
	v_mov_b32_e32 v24, v16
	v_mov_b32_e32 v25, v16
	v_mov_b32_e32 v26, v16
	v_mov_b32_e32 v27, v16
	v_mov_b32_e32 v20, v16
	v_mov_b32_e32 v21, v16
	v_mov_b32_e32 v22, v16
	v_mov_b32_e32 v23, v16
	s_branch .LBB0_265

; DEVI void phase11(const Params& P, int l, int pass, char* smem) {
;     ...
;     {
;       float4* rwp = reinterpret_cast<float4*>(red + w * 1024 + lane * 16);
; #pragma unroll
;       for (int q = 0; q < 4; ++q) rwp[q] = make_float4(oacc[2 * q].x, oacc[2 * q].y, oacc[2 * q + 1].x, oacc[2 * q + 1].y);
;     }
;     __syncthreads();
;     const int c = tid * 4;
;     float y[4];
;     {
;       float4 xx = *reinterpret_cast<const float4*>(xr + c);
;       float4 r0 = *reinterpret_cast<const float4*>(red + c);
;       float4 r1 = *reinterpret_cast<const float4*>(red + 1024 + c);
;       float4 r2 = *reinterpret_cast<const float4*>(red + 2048 + c);
;       float4 r3 = *reinterpret_cast<const float4*>(red + 3072 + c);
;       y[0] = ALPHA * xx.x + (r0.x + r1.x + r2.x + r3.x);
;       y[1] = ALPHA * xx.y + (r0.y + r1.y + r2.y + r3.y);
;       y[2] = ALPHA * xx.z + (r0.z + r1.z + r2.z + r3.z);
;       y[3] = ALPHA * xx.w + (r0.w + r1.w + r2.w + r3.w);
;     }
;     float s = wave_sum(y[0] + y[1] + y[2] + y[3]);
;     if (lane == 0) stat[w] = s;
.LBB0_271:
	v_lshl_add_u64 v[0:1], v[104:105], 2, s[54:55]
	ds_write_b128 v131, v[16:19] offset:13824
	ds_write_b128 v131, v[28:31] offset:13840
	ds_write_b128 v131, v[24:27] offset:13856
	ds_write_b128 v131, v[20:23] offset:13872
	s_waitcnt lgkmcnt(0)
	s_barrier
	s_add_i32 s56, s74, s23
	s_cmp_lt_i32 s56, s1
	s_cselect_b32 s56, s56, s74
	s_ashr_i32 s57, s56, 31
	s_lshl_b64 s[56:57], s[56:57], 13
	v_lshl_add_u64 v[218:219], v[102:103], 0, s[56:57]
	global_load_dwordx2 v[210:211], v[218:219], off sc1
	global_load_dwordx2 v[212:213], v[218:219], off offset:512 sc1
	global_load_dwordx2 v[214:215], v[218:219], off offset:1024 sc1
	global_load_dwordx2 v[216:217], v[218:219], off offset:1536 sc1
	ds_read_b128 v[8:11], v151 offset:13824
	ds_read_b128 v[12:15], v151 offset:17920
	ds_read_b128 v[16:19], v151 offset:22016
	ds_read_b128 v[20:23], v151 offset:26112
	s_waitcnt lgkmcnt(2)
	v_pk_add_f32 v[2:3], v[8:9], v[12:13]
	v_pk_add_f32 v[8:9], v[10:11], v[14:15]
	s_waitcnt lgkmcnt(1)
	v_pk_add_f32 v[2:3], v[2:3], v[16:17]
	v_pk_add_f32 v[8:9], v[8:9], v[18:19]
	s_waitcnt lgkmcnt(0)
	v_pk_add_f32 v[2:3], v[2:3], v[20:21]
	v_pk_add_f32 v[8:9], v[8:9], v[22:23]
	v_pk_fma_f32 v[4:5], v[228:229], s[92:93], v[2:3] op_sel_hi:[1,0,1]
	v_pk_fma_f32 v[2:3], v[230:231], s[92:93], v[8:9] op_sel_hi:[1,0,1]
	v_add_f32_e32 v6, v4, v5
	v_add_f32_e32 v6, v6, v2
	v_add_f32_e32 v6, v6, v3
	v_mov_b32_e32 v7, v6
	s_nop 1
	v_permlane32_swap_b32_e32 v7, v6
	s_nop 1
	v_add_f32_e32 v6, v6, v7
	v_mov_b32_e32 v7, v6
	s_nop 1
	v_permlane16_swap_b32_e32 v7, v6
	s_nop 1
	v_add_f32_e32 v6, v6, v7
	s_nop 1
	v_add_f32_dpp v7, v6, v6 row_ror:8 row_mask:0xf bank_mask:0xf
	s_nop 1
	v_add_f32_dpp v6, v7, v7 row_shl:4 row_mask:0xf bank_mask:0x5
	v_add_f32_dpp v6, v7, v7 row_shr:4 row_mask:0xf bank_mask:0xa
	s_nop 1
	v_add_f32_dpp v7, v6, v6 quad_perm:[2,3,0,1] row_mask:0xf bank_mask:0xf
	s_nop 1
	v_add_f32_dpp v6, v7, v7 quad_perm:[1,0,3,2] row_mask:0xf bank_mask:0xf
	s_and_saveexec_b64 s[54:55], s[52:53]
	s_cbranch_execz .LBB0_273
	ds_write_b32 v152, v6 offset:30208
